# FFN-up: conv weights of a tile loaded at the tile header (land during the K-loop), epilogue copies them instead of waiting on loads
# baseline (speedup 1.0000x reference)
.LBB0_2339:
	s_and_b32 s12, s15, 7
	v_lshl_add_u32 v0, s12, 8, v186
	v_ashrrev_i32_e32 v1, 31, v0
	v_lshlrev_b64 v[0:1], 11, v[0:1]
	s_and_b32 s12, s17, 0xffffff00
	v_lshl_add_u64 v[170:171], v[160:161], 0, v[0:1]
	v_add_u32_e32 v0, s12, v175
	s_and_b32 s12, s14, 7
	v_ashrrev_i32_e32 v1, 31, v0
	s_or_b32 s12, s12, s16
	v_lshlrev_b64 v[0:1], 11, v[0:1]
	s_lshl_b32 s13, s12, 8
	v_lshl_add_u64 v[172:173], v[168:169], 0, v[0:1]
	v_add_u32_e32 v0, s13, v175
	s_lshl_b32 s12, s14, 5
	v_ashrrev_i32_e32 v1, 31, v0
	s_and_b32 s12, s12, 0xffffff00
	v_lshlrev_b64 v[0:1], 11, v[0:1]
	v_add_u32_e32 v2, s12, v175
	v_or_b32_e32 v233, s12, v174
	v_ashrrev_i32_e32 v233, 1, v233
	v_or_b32_e32 v233, v233, v154
	v_lshlrev_b32_e32 v233, 2, v233
	global_load_dword v222, v233, s[10:11]
	s_add_u32 vcc_lo, s10, 0x5800
	s_addc_u32 vcc_hi, s11, 0
	global_load_dword v223, v233, vcc
	s_add_u32 vcc_lo, s10, 0xb000
	s_addc_u32 vcc_hi, s11, 0
	global_load_dword v224, v233, vcc
	s_add_u32 vcc_lo, s10, 0x2c00
	s_addc_u32 vcc_hi, s11, 0
	global_load_dword v225, v233, vcc
	s_add_u32 vcc_lo, s10, 0x8400
	s_addc_u32 vcc_hi, s11, 0
	global_load_dword v226, v233, vcc
	s_add_u32 vcc_lo, s10, 0xdc00
	s_addc_u32 vcc_hi, s11, 0
	global_load_dword v227, v233, vcc
	s_cmp_eq_u32 s101, 0
	s_cbranch_scc1 .Lpf_cold_up
	s_mov_b32 s101, 0
	s_branch .Lpf_after_up

.LBB0_2340:
	s_and_b32 s19, s18, 0x18000
	v_add_u32_e32 v187, s19, v180
	s_add_i32 s19, s18, 0xfffe8000
	s_and_b32 s19, s19, 0x18000
	v_or_b32_e32 v212, s19, v179
	v_add_u32_e32 v213, s19, v176
	s_waitcnt lgkmcnt(0)
	v_mfma_f32_32x32x16_bf16 v[112:127], v[150:153], v[142:145], v[112:127]
	v_mfma_f32_32x32x16_bf16 v[96:111], v[150:153], v[130:133], v[96:111]
	s_waitcnt vmcnt(8)
	s_barrier
	v_add_u32_e32 v192, v212, v177
	v_add_u32_e32 v208, v213, v177
	ds_read_b128 v[188:191], v192 offset:16384
	ds_read_b128 v[192:195], v192 offset:18432
	ds_read_b128 v[196:199], v208
	v_mfma_f32_32x32x16_bf16 v[80:95], v[146:149], v[142:145], v[80:95]
	v_mfma_f32_32x32x16_bf16 v[64:79], v[146:149], v[130:133], v[64:79]
	ds_read_b128 v[200:203], v208 offset:2048
	v_readfirstlane_b32 s19, v187
	s_mov_b32 m0, s19
	s_nop 0
	global_load_lds_dwordx4 v[170:171], off
	v_mfma_f32_32x32x16_bf16 v[48:63], v[138:141], v[142:145], v[48:63]
	v_mfma_f32_32x32x16_bf16 v[32:47], v[138:141], v[130:133], v[32:47]
	ds_read_b128 v[204:207], v208 offset:4096
	s_add_i32 s20, s19, 0x2000
	v_lshl_add_u64 v[150:151], v[170:171], 0, s[34:35]
	s_mov_b32 m0, s20
	s_nop 0
	global_load_lds_dwordx4 v[150:151], off
	v_mfma_f32_32x32x16_bf16 v[16:31], v[134:137], v[142:145], v[16:31]
	v_mfma_f32_32x32x16_bf16 v[0:15], v[134:137], v[130:133], v[0:15]
	ds_read_b128 v[208:211], v208 offset:6144
	s_waitcnt lgkmcnt(3)
	v_mfma_f32_32x32x16_bf16 v[112:127], v[196:199], v[188:191], v[112:127]
	v_add_u32_e32 v130, v212, v178
	v_add_u32_e32 v134, v213, v178
	ds_read_b128 v[142:145], v130 offset:16384
	v_mfma_f32_32x32x16_bf16 v[96:111], v[196:199], v[192:195], v[96:111]
	ds_read_b128 v[130:133], v130 offset:18432
	s_add_i32 s20, s19, 0x6000
	s_addk_i32 s19, 0x4000
	s_mov_b32 m0, s19
	s_nop 0
	global_load_lds_dwordx4 v[172:173], off
	s_waitcnt lgkmcnt(4)
	v_mfma_f32_32x32x16_bf16 v[80:95], v[200:203], v[188:191], v[80:95]
	ds_read_b128 v[150:153], v134
	v_mfma_f32_32x32x16_bf16 v[64:79], v[200:203], v[192:195], v[64:79]
	ds_read_b128 v[146:149], v134 offset:2048
	s_waitcnt lgkmcnt(5)
	v_mfma_f32_32x32x16_bf16 v[48:63], v[204:207], v[188:191], v[48:63]
	ds_read_b128 v[138:141], v134 offset:4096
	v_mfma_f32_32x32x16_bf16 v[32:47], v[204:207], v[192:195], v[32:47]
	ds_read_b128 v[134:137], v134 offset:6144
	v_lshl_add_u64 v[212:213], v[172:173], 0, s[34:35]
	s_mov_b32 m0, s20
	s_nop 0
	global_load_lds_dwordx4 v[212:213], off
	s_waitcnt lgkmcnt(6)
	v_mfma_f32_32x32x16_bf16 v[16:31], v[208:211], v[188:191], v[16:31]
	s_add_i32 s18, s18, 0x8000
	v_lshl_add_u64 v[170:171], v[170:171], 0, 64
	v_lshl_add_u64 v[172:173], v[172:173], 0, 64
	s_cmp_eq_u32 s18, 0x100000
	v_mfma_f32_32x32x16_bf16 v[0:15], v[208:211], v[192:195], v[0:15]
	s_cbranch_scc0 .LBB0_2340
	s_waitcnt vmcnt(8) lgkmcnt(0)
	s_barrier
	v_add_u32_e32 v187, v179, v177
	ds_read_b128 v[170:173], v187 offset:49152
	ds_read_b128 v[188:191], v187 offset:51200
	v_add_u32_e32 v187, v176, v177
	ds_read_b128 v[192:195], v187 offset:32768
	ds_read_b128 v[196:199], v187 offset:34816
	ds_read_b128 v[200:203], v187 offset:36864
	ds_read_b128 v[204:207], v187 offset:38912
	s_waitcnt lgkmcnt(9)
	v_mfma_f32_32x32x16_bf16 v[112:127], v[150:153], v[142:145], v[112:127]
	v_mfma_f32_32x32x16_bf16 v[96:111], v[150:153], v[130:133], v[96:111]
	s_waitcnt lgkmcnt(8)
	v_mfma_f32_32x32x16_bf16 v[80:95], v[146:149], v[142:145], v[80:95]
	v_mfma_f32_32x32x16_bf16 v[64:79], v[146:149], v[130:133], v[64:79]
	s_waitcnt lgkmcnt(7)
	v_mfma_f32_32x32x16_bf16 v[48:63], v[138:141], v[142:145], v[48:63]
	v_mfma_f32_32x32x16_bf16 v[32:47], v[138:141], v[130:133], v[32:47]
	s_waitcnt lgkmcnt(6)
	v_mfma_f32_32x32x16_bf16 v[16:31], v[134:137], v[142:145], v[16:31]
	v_mfma_f32_32x32x16_bf16 v[0:15], v[134:137], v[130:133], v[0:15]
	v_add_u32_e32 v134, v179, v178
	v_add_u32_e32 v150, v176, v178
	ds_read_b128 v[130:133], v134 offset:49152
	ds_read_b128 v[134:137], v134 offset:51200
	ds_read_b128 v[138:141], v150 offset:32768
	ds_read_b128 v[142:145], v150 offset:34816
	ds_read_b128 v[146:149], v150 offset:36864
	ds_read_b128 v[150:153], v150 offset:38912
	s_waitcnt lgkmcnt(9)
	v_mfma_f32_32x32x16_bf16 v[112:127], v[192:195], v[170:173], v[112:127]
	v_mfma_f32_32x32x16_bf16 v[96:111], v[192:195], v[188:191], v[96:111]
	s_waitcnt lgkmcnt(8)
	v_mfma_f32_32x32x16_bf16 v[80:95], v[196:199], v[170:173], v[80:95]
	v_mfma_f32_32x32x16_bf16 v[64:79], v[196:199], v[188:191], v[64:79]
	s_waitcnt lgkmcnt(7)
	v_mfma_f32_32x32x16_bf16 v[48:63], v[200:203], v[170:173], v[48:63]
	v_mfma_f32_32x32x16_bf16 v[32:47], v[200:203], v[188:191], v[32:47]
	s_waitcnt vmcnt(4) lgkmcnt(0)
	s_barrier
	v_add_u32_e32 v187, v184, v177
	s_waitcnt lgkmcnt(6)
	v_mfma_f32_32x32x16_bf16 v[16:31], v[204:207], v[170:173], v[16:31]
	v_mfma_f32_32x32x16_bf16 v[0:15], v[204:207], v[188:191], v[0:15]
	ds_read_b128 v[170:173], v187 offset:16384
	ds_read_b128 v[188:191], v187 offset:18432
	v_add_u32_e32 v187, v185, v177
	ds_read_b128 v[192:195], v187
	ds_read_b128 v[196:199], v187 offset:2048
	ds_read_b128 v[200:203], v187 offset:4096
	ds_read_b128 v[204:207], v187 offset:6144
	s_waitcnt lgkmcnt(9)
	v_mfma_f32_32x32x16_bf16 v[112:127], v[138:141], v[130:133], v[112:127]
	v_mfma_f32_32x32x16_bf16 v[96:111], v[138:141], v[134:137], v[96:111]
	s_waitcnt lgkmcnt(8)
	v_mfma_f32_32x32x16_bf16 v[80:95], v[142:145], v[130:133], v[80:95]
	v_mfma_f32_32x32x16_bf16 v[64:79], v[142:145], v[134:137], v[64:79]
	s_waitcnt lgkmcnt(7)
	v_mfma_f32_32x32x16_bf16 v[48:63], v[146:149], v[130:133], v[48:63]
	v_mfma_f32_32x32x16_bf16 v[32:47], v[146:149], v[134:137], v[32:47]
	s_waitcnt lgkmcnt(6)
	v_mfma_f32_32x32x16_bf16 v[16:31], v[150:153], v[130:133], v[16:31]
	v_mfma_f32_32x32x16_bf16 v[0:15], v[150:153], v[134:137], v[0:15]
	v_add_u32_e32 v134, v184, v178
	v_add_u32_e32 v150, v185, v178
	ds_read_b128 v[130:133], v134 offset:16384
	ds_read_b128 v[134:137], v134 offset:18432
	ds_read_b128 v[138:141], v150
	ds_read_b128 v[142:145], v150 offset:2048
	ds_read_b128 v[146:149], v150 offset:4096
	ds_read_b128 v[150:153], v150 offset:6144
	s_waitcnt lgkmcnt(9)
	v_mfma_f32_32x32x16_bf16 v[112:127], v[192:195], v[170:173], v[112:127]
	v_mfma_f32_32x32x16_bf16 v[96:111], v[192:195], v[188:191], v[96:111]
	s_waitcnt lgkmcnt(8)
	v_mfma_f32_32x32x16_bf16 v[80:95], v[196:199], v[170:173], v[80:95]
	v_mfma_f32_32x32x16_bf16 v[64:79], v[196:199], v[188:191], v[64:79]
	s_waitcnt lgkmcnt(7)
	v_mfma_f32_32x32x16_bf16 v[48:63], v[200:203], v[170:173], v[48:63]
	v_mfma_f32_32x32x16_bf16 v[32:47], v[200:203], v[188:191], v[32:47]
	s_waitcnt vmcnt(0) lgkmcnt(0)
	s_barrier
	v_add_u32_e32 v187, v182, v177
	s_waitcnt lgkmcnt(6)
	v_mfma_f32_32x32x16_bf16 v[16:31], v[204:207], v[170:173], v[16:31]
	v_mfma_f32_32x32x16_bf16 v[0:15], v[204:207], v[188:191], v[0:15]
	ds_read_b128 v[170:173], v187 offset:16384
	ds_read_b128 v[188:191], v187 offset:18432
	v_add_u32_e32 v187, v183, v177
	ds_read_b128 v[192:195], v187
	ds_read_b128 v[196:199], v187 offset:2048
	ds_read_b128 v[200:203], v187 offset:4096
	ds_read_b128 v[204:207], v187 offset:6144
	s_waitcnt lgkmcnt(9)
	v_mfma_f32_32x32x16_bf16 v[112:127], v[138:141], v[130:133], v[112:127]
	v_mfma_f32_32x32x16_bf16 v[96:111], v[138:141], v[134:137], v[96:111]
	s_waitcnt lgkmcnt(8)
	v_mfma_f32_32x32x16_bf16 v[80:95], v[142:145], v[130:133], v[80:95]
	v_mfma_f32_32x32x16_bf16 v[64:79], v[142:145], v[134:137], v[64:79]
	s_waitcnt lgkmcnt(7)
	v_mfma_f32_32x32x16_bf16 v[48:63], v[146:149], v[130:133], v[48:63]
	v_mfma_f32_32x32x16_bf16 v[32:47], v[146:149], v[134:137], v[32:47]
	s_waitcnt lgkmcnt(6)
	v_mfma_f32_32x32x16_bf16 v[16:31], v[150:153], v[130:133], v[16:31]
	v_mfma_f32_32x32x16_bf16 v[0:15], v[150:153], v[134:137], v[0:15]
	v_add_u32_e32 v134, v182, v178
	v_add_u32_e32 v150, v183, v178
	ds_read_b128 v[130:133], v134 offset:16384
	ds_read_b128 v[134:137], v134 offset:18432
	ds_read_b128 v[138:141], v150
	ds_read_b128 v[142:145], v150 offset:2048
	ds_read_b128 v[146:149], v150 offset:4096
	ds_read_b128 v[150:153], v150 offset:6144
	s_waitcnt lgkmcnt(9)
	v_mfma_f32_32x32x16_bf16 v[112:127], v[192:195], v[170:173], v[112:127]
	v_mfma_f32_32x32x16_bf16 v[96:111], v[192:195], v[188:191], v[96:111]
	s_waitcnt lgkmcnt(8)
	v_mfma_f32_32x32x16_bf16 v[80:95], v[196:199], v[170:173], v[80:95]
	v_mfma_f32_32x32x16_bf16 v[64:79], v[196:199], v[188:191], v[64:79]
	s_waitcnt lgkmcnt(7)
	v_mfma_f32_32x32x16_bf16 v[48:63], v[200:203], v[170:173], v[48:63]
	v_mfma_f32_32x32x16_bf16 v[32:47], v[200:203], v[188:191], v[32:47]
	s_waitcnt lgkmcnt(6)
	v_mfma_f32_32x32x16_bf16 v[16:31], v[204:207], v[170:173], v[16:31]
	v_mfma_f32_32x32x16_bf16 v[0:15], v[204:207], v[188:191], v[0:15]
	s_waitcnt lgkmcnt(3)
	v_mfma_f32_32x32x16_bf16 v[112:127], v[138:141], v[130:133], v[112:127]
	s_waitcnt lgkmcnt(2)
	v_mfma_f32_32x32x16_bf16 v[80:95], v[142:145], v[130:133], v[80:95]
	s_waitcnt lgkmcnt(1)
	v_mfma_f32_32x32x16_bf16 v[48:63], v[146:149], v[130:133], v[48:63]
	s_waitcnt lgkmcnt(0)
	v_mfma_f32_32x32x16_bf16 v[16:31], v[150:153], v[130:133], v[16:31]
	v_or_b32_e32 v132, s12, v174
	v_ashrrev_i32_e32 v130, 1, v132
	v_or_b32_e32 v130, v130, v154
	v_ashrrev_i32_e32 v131, 31, v130
	s_movk_i32 s12, 0x5000
	v_mfma_f32_32x32x16_bf16 v[96:111], v[138:141], v[134:137], v[96:111]
	v_mfma_f32_32x32x16_bf16 v[64:79], v[142:145], v[134:137], v[64:79]
	v_add_u32_e32 v142, s13, v155
	s_mov_b32 s13, 0xb000
	v_ashrrev_i32_e32 v133, 7, v142
	v_mfma_f32_32x32x16_bf16 v[32:47], v[146:149], v[134:137], v[32:47]
	v_mfma_f32_32x32x16_bf16 v[0:15], v[150:153], v[134:137], v[0:15]
	v_lshl_add_u64 v[134:135], v[130:131], 2, s[10:11]
	v_add_co_u32_e32 v138, vcc, s12, v134
	s_mov_b32 s12, 0x8000
	s_nop 0
	v_addc_co_u32_e32 v139, vcc, 0, v135, vcc
	v_add_co_u32_e32 v138, vcc, s13, v134
	s_nop 0
	s_nop 0
	v_addc_co_u32_e32 v139, vcc, 0, v135, vcc
	v_add_co_u32_e32 v140, vcc, s47, v134
	s_nop 0
	s_nop 0
	v_addc_co_u32_e32 v141, vcc, 0, v135, vcc
	v_add_co_u32_e32 v140, vcc, s12, v134
	s_mov_b32 s12, 0xd000
	s_nop 0
	v_addc_co_u32_e32 v141, vcc, 0, v135, vcc
	v_add_co_u32_e32 v134, vcc, s12, v134
	s_nop 0
	s_nop 0
	v_addc_co_u32_e32 v135, vcc, 0, v135, vcc
	v_mov_b32_e32 v136, v222
	v_mov_b32_e32 v137, v223
	v_mov_b32_e32 v138, v225
	v_mov_b32_e32 v139, v224
	v_mov_b32_e32 v140, v226
	v_mov_b32_e32 v141, v227
	v_readlane_b32 s100, v252, 7
	s_add_i32 s100, s14, s100
	s_cmpk_lt_i32 s100, 0xb0
	s_cbranch_scc0 .Lpf_none_up
	s_and_b32 vcc_lo, s100, 7
	s_or_b32 vcc_lo, vcc_lo, s16
	s_lshl_b32 vcc_lo, vcc_lo, 8
	v_add_u32_e32 v238, vcc_lo, v175
	v_ashrrev_i32_e32 v239, 31, v238
	v_lshlrev_b64 v[238:239], 11, v[238:239]
	v_lshl_add_u64 v[238:239], v[156:157], 0, v[238:239]
	s_lshl_b32 vcc_lo, s100, 5
	s_and_b32 vcc_lo, vcc_lo, 0xffffff00
	v_add_u32_e32 v240, vcc_lo, v175
	v_ashrrev_i32_e32 v241, 31, v240
	v_lshlrev_b64 v[240:241], 11, v[240:241]
	v_lshl_add_u64 v[240:241], v[158:159], 0, v[240:241]
	v_readfirstlane_b32 s100, v180
	s_mov_b32 m0, s100
	s_nop 0
	global_load_lds_dwordx4 v[238:239], off
	v_lshl_add_u64 v[242:243], v[238:239], 0, s[34:35]
	s_add_i32 m0, s100, 0x2000
	s_nop 0
	global_load_lds_dwordx4 v[242:243], off
	s_add_i32 m0, s100, 0x4000
	s_nop 0
	global_load_lds_dwordx4 v[240:241], off
	v_lshl_add_u64 v[242:243], v[240:241], 0, s[34:35]
	s_add_i32 m0, s100, 0x6000
	s_nop 0
	global_load_lds_dwordx4 v[242:243], off
	v_lshl_add_u64 v[242:243], v[238:239], 0, 64
	s_add_i32 m0, s100, 0x8000
	s_nop 0
	global_load_lds_dwordx4 v[242:243], off
	s_mov_b64 vcc, 0x40040
	v_lshl_add_u64 v[242:243], v[238:239], 0, vcc
	s_add_i32 m0, s100, 0xa000
	s_nop 0
	global_load_lds_dwordx4 v[242:243], off
	v_lshl_add_u64 v[242:243], v[240:241], 0, 64
	s_add_i32 m0, s100, 0xc000
	s_nop 0
	global_load_lds_dwordx4 v[242:243], off
	s_mov_b64 vcc, 0x40040
	v_lshl_add_u64 v[242:243], v[240:241], 0, vcc
	s_add_i32 m0, s100, 0xe000
	s_nop 0
	global_load_lds_dwordx4 v[242:243], off
	s_mov_b64 vcc, 0x80
	v_lshl_add_u64 v[242:243], v[238:239], 0, vcc
	s_add_i32 m0, s100, 0x10000
	s_nop 0
	global_load_lds_dwordx4 v[242:243], off
	s_mov_b64 vcc, 0x40080
	v_lshl_add_u64 v[242:243], v[238:239], 0, vcc
	s_add_i32 m0, s100, 0x12000
	s_nop 0
	global_load_lds_dwordx4 v[242:243], off
	s_mov_b64 vcc, 0x80
	v_lshl_add_u64 v[242:243], v[240:241], 0, vcc
	s_add_i32 m0, s100, 0x14000
	s_nop 0
	global_load_lds_dwordx4 v[242:243], off
	s_mov_b64 vcc, 0x40080
	v_lshl_add_u64 v[242:243], v[240:241], 0, vcc
	s_add_i32 m0, s100, 0x16000
	s_nop 0
	global_load_lds_dwordx4 v[242:243], off
	s_mov_b32 s101, 1
	s_branch .Lpf_done_up
